# norm row loop: rows r=1,3 reuse the modulation rows loaded for r=0,2 (same 4096-row block), 16 fewer loads per iteration
# speedup vs baseline: 1.0051x; 1.0030x over previous
.LBB0_741:
	s_lshl_b64 s[16:17], s[16:17], 12
	s_waitcnt lgkmcnt(0)
	s_add_u32 s14, s14, s16
	s_addc_u32 s15, s15, s17
	global_load_dwordx4 v[200:203], v208, s[14:15]
	global_load_dwordx4 v[184:187], v208, s[14:15] offset:1024
	global_load_dwordx4 v[176:179], v208, s[14:15] offset:2048
	global_load_dwordx4 v[164:167], v208, s[14:15] offset:3072
	s_and_b64 vcc, exec, s[0:1]
	s_cbranch_vccnz .LBB0_743
	s_add_i32 s11, s12, 0xffffc000
	s_lshr_b32 s11, s11, 2
	s_ashr_i32 s9, s12, 12
	s_add_i32 s11, s11, 4
	s_cmpk_lt_i32 s12, 0x4000
	s_cselect_b32 s9, s9, s11
	s_mul_hi_i32 s11, s9, 0x6000
	s_mulk_i32 s9, 0x6000
	s_add_u32 s12, s31, s9
	s_addc_u32 s13, s34, s11
	s_waitcnt vmcnt(0)
	v_lshl_add_u64 v[48:49], s[12:13], 0, v[208:209]
	s_mov_b64 s[14:15], 0x1000
	v_add_co_u32_e32 v58, vcc, 0x1000, v48
	v_lshl_add_u64 v[56:57], v[48:49], 0, s[14:15]
	s_nop 0
	v_addc_co_u32_e32 v59, vcc, 0, v49, vcc
.LBB0_743:
	s_add_i32 s14, s35, s10
	s_cmpk_lt_i32 s14, 0x4200
	s_cselect_b64 s[18:19], -1, 0
	s_and_b64 s[12:13], s[18:19], exec
	s_cselect_b32 s12, s14, s10
	s_and_b64 vcc, exec, s[2:3]
	s_mov_b64 s[16:17], -1
	s_cbranch_vccnz .LBB0_745
	s_ashr_i32 s13, s12, 31
	s_mov_b64 s[16:17], 0
	s_mov_b64 s[22:23], s[12:13]

.LBB0_761:
	s_waitcnt vmcnt(0)
	v_mov_b64_e32 v[104:105], v[120:121]
	v_mov_b64_e32 v[106:107], v[122:123]
	v_mov_b64_e32 v[108:109], v[124:125]
	v_mov_b64_e32 v[110:111], v[126:127]
	v_mov_b64_e32 v[52:53], v[68:69]
	v_mov_b64_e32 v[54:55], v[70:71]
	v_mov_b64_e32 v[48:49], v[64:65]
	v_mov_b64_e32 v[50:51], v[66:67]
	v_mov_b64_e32 v[60:61], v[80:81]
	v_mov_b64_e32 v[62:63], v[82:83]
	v_mov_b64_e32 v[56:57], v[72:73]
	v_mov_b64_e32 v[58:59], v[74:75]
	v_mov_b64_e32 v[132:133], v[140:141]
	v_mov_b64_e32 v[134:135], v[142:143]
	v_mov_b64_e32 v[128:129], v[136:137]
	v_mov_b64_e32 v[130:131], v[138:139]
	v_mov_b64_e32 v[76:77], v[88:89]
	v_mov_b64_e32 v[78:79], v[90:91]
	v_mov_b64_e32 v[84:85], v[92:93]
	v_mov_b64_e32 v[86:87], v[94:95]
	v_mov_b64_e32 v[20:21], v[36:37]
	v_mov_b64_e32 v[22:23], v[38:39]
	v_mov_b64_e32 v[16:17], v[32:33]
	v_mov_b64_e32 v[18:19], v[34:35]
	v_mov_b64_e32 v[28:29], v[44:45]
	v_mov_b64_e32 v[30:31], v[46:47]
	v_mov_b64_e32 v[24:25], v[40:41]
	v_mov_b64_e32 v[26:27], v[42:43]
	v_mov_b64_e32 v[100:101], v[116:117]
	v_mov_b64_e32 v[102:103], v[118:119]
	v_mov_b64_e32 v[96:97], v[112:113]
	v_mov_b64_e32 v[98:99], v[114:115]
	v_pk_mul_f32 v[220:221], v[206:207], v[206:207]
	v_pk_mul_f32 v[224:225], v[204:205], v[204:205]
	v_mul_f32_e32 v208, v172, v172
	v_pk_mov_b32 v[240:241], v[224:225], v[220:221] op_sel:[1,0]
	v_mov_b32_e32 v225, v221
	v_pk_add_f32 v[220:221], v[240:241], v[224:225]
	v_pk_mul_f32 v[224:225], v[190:191], v[190:191]
	v_pk_mul_f32 v[240:241], v[188:189], v[188:189]
	v_mul_f32_e32 v210, v173, v173
	v_pk_mov_b32 v[242:243], v[240:241], v[224:225] op_sel:[1,0]
	v_mov_b32_e32 v241, v225
	v_pk_add_f32 v[224:225], v[242:243], v[240:241]
	v_pk_add_f32 v[220:221], v[220:221], v[220:221] op_sel:[0,1] op_sel_hi:[1,0]
	v_pk_add_f32 v[224:225], v[224:225], v[224:225] op_sel:[0,1] op_sel_hi:[1,0]
	v_mov_b32_e32 v221, v208
	v_mov_b32_e32 v225, v210
	v_mul_f32_e32 v208, v181, v181
	v_pk_add_f32 v[220:221], v[220:221], v[224:225]
	v_pk_fma_f32 v[224:225], v[180:181], v[180:181], v[208:209] op_sel_hi:[1,1,0]
	v_mul_f32_e32 v208, v183, v183
	v_mul_f32_e32 v211, v174, v174
	v_mul_f32_e32 v223, v175, v175
	v_pk_fma_f32 v[240:241], v[182:183], v[182:183], v[208:209] op_sel_hi:[1,1,0]
	v_mov_b32_e32 v225, v211
	v_mov_b32_e32 v241, v223
	v_pk_add_f32 v[224:225], v[224:225], v[240:241]
	v_mul_f32_e32 v210, v201, v201
	v_mul_f32_e32 v211, v203, v203
	v_pk_add_f32 v[220:221], v[220:221], v[224:225]
	v_fmac_f32_e32 v210, v200, v200
	v_fmac_f32_e32 v211, v202, v202
	v_add_f32_e32 v208, v220, v221
	v_add_f32_e32 v210, v210, v211
	v_mul_f32_e32 v211, v185, v185
	v_mul_f32_e32 v220, v187, v187
	v_fmac_f32_e32 v211, v184, v184
	v_fmac_f32_e32 v220, v186, v186
	v_add_f32_e32 v211, v211, v220
	v_add_f32_e32 v210, v210, v211
	v_mul_f32_e32 v211, v177, v177
	v_mul_f32_e32 v220, v179, v179
	v_fmac_f32_e32 v211, v176, v176
	v_fmac_f32_e32 v220, v178, v178
	v_add_f32_e32 v211, v211, v220
	v_add_f32_e32 v210, v210, v211
	v_mul_f32_e32 v211, v165, v165
	v_mul_f32_e32 v220, v167, v167
	v_fmac_f32_e32 v211, v164, v164
	v_fmac_f32_e32 v220, v166, v166
	v_add_f32_e32 v211, v211, v220
	v_add_f32_e32 v210, v210, v211
	v_mul_f32_e32 v211, v197, v197
	v_mul_f32_e32 v220, v199, v199
	v_fmac_f32_e32 v211, v196, v196
	v_fmac_f32_e32 v220, v198, v198
	v_add_f32_e32 v211, v211, v220
	v_mul_f32_e32 v220, v169, v169
	v_mul_f32_e32 v221, v171, v171
	v_fmac_f32_e32 v220, v168, v168
	v_fmac_f32_e32 v221, v170, v170
	v_add_f32_e32 v220, v220, v221
	v_add_f32_e32 v211, v211, v220
	v_mul_f32_e32 v220, v161, v161
	v_mul_f32_e32 v221, v163, v163
	v_fmac_f32_e32 v220, v160, v160
	v_fmac_f32_e32 v221, v162, v162
	v_add_f32_e32 v220, v220, v221
	v_add_f32_e32 v211, v211, v220
	v_mul_f32_e32 v220, v153, v153
	v_mul_f32_e32 v221, v155, v155
	v_fmac_f32_e32 v220, v152, v152
	v_fmac_f32_e32 v221, v154, v154
	v_add_f32_e32 v220, v220, v221
	v_add_f32_e32 v211, v211, v220
	v_mul_f32_e32 v220, v193, v193
	v_mul_f32_e32 v221, v195, v195
	v_fmac_f32_e32 v220, v192, v192
	v_fmac_f32_e32 v221, v194, v194
	v_add_f32_e32 v220, v220, v221
	v_mul_f32_e32 v221, v157, v157
	v_mul_f32_e32 v223, v159, v159
	v_fmac_f32_e32 v221, v156, v156
	v_fmac_f32_e32 v223, v158, v158
	v_add_f32_e32 v221, v221, v223
	v_add_f32_e32 v220, v220, v221
	v_mul_f32_e32 v221, v149, v149
	v_mul_f32_e32 v223, v151, v151
	v_fmac_f32_e32 v221, v148, v148
	v_fmac_f32_e32 v223, v150, v150
	v_add_f32_e32 v221, v221, v223
	v_add_f32_e32 v220, v220, v221
	v_mul_f32_e32 v221, v145, v145
	v_mul_f32_e32 v223, v147, v147
	v_fmac_f32_e32 v221, v144, v144
	v_fmac_f32_e32 v223, v146, v146
	v_add_f32_e32 v221, v221, v223
	ds_bpermute_b32 v223, v215, v208
	ds_bpermute_b32 v224, v215, v210
	v_add_f32_e32 v220, v220, v221
	ds_bpermute_b32 v221, v215, v220
	ds_bpermute_b32 v225, v215, v211
	s_waitcnt lgkmcnt(3)
	v_add_f32_e32 v208, v208, v223
	ds_bpermute_b32 v223, v236, v208
	s_waitcnt lgkmcnt(3)
	v_add_f32_e32 v210, v210, v224
	ds_bpermute_b32 v224, v236, v210
	s_waitcnt lgkmcnt(3)
	v_add_f32_e32 v220, v220, v221
	ds_bpermute_b32 v221, v236, v220
	s_waitcnt lgkmcnt(2)
	v_add_f32_e32 v208, v208, v223
	ds_bpermute_b32 v223, v237, v208
	v_add_f32_e32 v211, v211, v225
	ds_bpermute_b32 v225, v236, v211
	s_waitcnt lgkmcnt(3)
	v_add_f32_e32 v210, v210, v224
	ds_bpermute_b32 v224, v237, v210
	s_waitcnt lgkmcnt(2)
	v_add_f32_e32 v208, v208, v223
	v_add_f32_e32 v220, v220, v221
	ds_bpermute_b32 v223, v238, v208
	ds_bpermute_b32 v221, v237, v220
	s_waitcnt lgkmcnt(3)
	v_add_f32_e32 v211, v211, v225
	ds_bpermute_b32 v225, v237, v211
	s_waitcnt lgkmcnt(3)
	v_add_f32_e32 v210, v210, v224
	s_waitcnt lgkmcnt(2)
	v_add_f32_e32 v208, v208, v223
	ds_bpermute_b32 v224, v238, v210
	s_waitcnt lgkmcnt(2)
	v_add_f32_e32 v220, v220, v221
	ds_bpermute_b32 v223, v233, v208
	ds_bpermute_b32 v221, v238, v220
	s_waitcnt lgkmcnt(3)
	v_add_f32_e32 v211, v211, v225
	ds_bpermute_b32 v225, v238, v211
	s_waitcnt lgkmcnt(3)
	v_add_f32_e32 v210, v210, v224
	s_waitcnt lgkmcnt(2)
	v_add_f32_e32 v230, v208, v223
	s_waitcnt lgkmcnt(1)
	v_add_f32_e32 v220, v220, v221
	ds_bpermute_b32 v221, v233, v210
	ds_bpermute_b32 v232, v234, v230
	s_waitcnt lgkmcnt(2)
	v_add_f32_e32 v211, v211, v225
	ds_bpermute_b32 v229, v233, v220
	ds_bpermute_b32 v224, v233, v211
	s_waitcnt lgkmcnt(3)
	v_add_f32_e32 v225, v210, v221
	s_waitcnt lgkmcnt(2)
	v_add_f32_e32 v210, v230, v232
	v_fmamk_f32 v210, v210, 0x3a800000, v222
	s_waitcnt lgkmcnt(1)
	v_add_f32_e32 v208, v220, v229
	v_rsq_f32_e32 v220, v210
	s_waitcnt lgkmcnt(0)
	v_add_f32_e32 v223, v211, v224
	ds_bpermute_b32 v229, v234, v225
	ds_bpermute_b32 v224, v234, v223
	ds_bpermute_b32 v239, v234, v208
	v_mov_b32_e32 v221, v220
	v_pk_mul_f32 v[204:205], v[204:205], v[220:221] op_sel_hi:[1,0]
	v_pk_mul_f32 v[206:207], v[206:207], v[220:221] op_sel_hi:[1,0]
	s_ashr_i32 s11, s10, 31
	v_pk_mul_f32 v[206:207], v[2:3], v[206:207]
	v_pk_mul_f32 v[204:205], v[0:1], v[204:205]
	s_mov_b64 s[2:3], -1
	s_and_b64 vcc, exec, s[0:1]
	v_pk_mul_f32 v[188:189], v[188:189], v[220:221]
	v_pk_mul_f32 v[180:181], v[180:181], v[220:221]
	v_pk_mul_f32 v[172:173], v[172:173], v[220:221]
	s_cbranch_vccnz .LBB0_764
	v_pk_add_f32 v[240:241], v[82:83], 1.0 op_sel_hi:[1,0]
	v_pk_add_f32 v[242:243], v[80:81], 1.0 op_sel_hi:[1,0]
	s_lshl_b64 s[2:3], s[10:11], 11
	v_pk_fma_f32 v[240:241], v[240:241], v[206:207], v[122:123]
	v_pk_fma_f32 v[242:243], v[242:243], v[204:205], v[120:121]
	v_mov_b32_e32 v221, v220
	v_cvt_pk_bf16_f32 v242, v242, v243
	v_cvt_pk_bf16_f32 v243, v240, v241
	v_lshl_add_u64 v[240:241], v[216:217], 0, s[2:3]
	global_store_dwordx2 v[240:241], v[242:243], off
	v_pk_mul_f32 v[242:243], v[190:191], v[220:221]
	v_pk_mul_f32 v[244:245], v[4:5], v[188:189]
	v_pk_mul_f32 v[242:243], v[6:7], v[242:243]
	v_pk_add_f32 v[246:247], v[70:71], 1.0 op_sel_hi:[1,0]
	v_pk_add_f32 v[248:249], v[68:69], 1.0 op_sel_hi:[1,0]
	v_pk_fma_f32 v[242:243], v[246:247], v[242:243], v[126:127]
	v_pk_fma_f32 v[244:245], v[248:249], v[244:245], v[124:125]
	v_pk_add_f32 v[246:247], v[66:67], 1.0 op_sel_hi:[1,0]
	v_cvt_pk_bf16_f32 v244, v244, v245
	v_cvt_pk_bf16_f32 v245, v242, v243
	v_pk_mul_f32 v[242:243], v[182:183], v[220:221]
	global_store_dwordx2 v[240:241], v[244:245], off offset:512
	v_pk_mul_f32 v[242:243], v[10:11], v[242:243]
	v_pk_mul_f32 v[244:245], v[8:9], v[180:181]
	v_pk_add_f32 v[248:249], v[64:65], 1.0 op_sel_hi:[1,0]
	v_pk_fma_f32 v[242:243], v[246:247], v[242:243], v[142:143]
	v_pk_fma_f32 v[244:245], v[248:249], v[244:245], v[140:141]
	v_pk_add_f32 v[246:247], v[74:75], 1.0 op_sel_hi:[1,0]
	v_cvt_pk_bf16_f32 v244, v244, v245
	v_cvt_pk_bf16_f32 v245, v242, v243
	v_pk_mul_f32 v[242:243], v[174:175], v[220:221]
	global_store_dwordx2 v[240:241], v[244:245], off offset:1024
	v_pk_mul_f32 v[242:243], v[14:15], v[242:243]
	v_pk_mul_f32 v[244:245], v[12:13], v[172:173]
	v_pk_add_f32 v[248:249], v[72:73], 1.0 op_sel_hi:[1,0]
	v_pk_fma_f32 v[242:243], v[246:247], v[242:243], v[138:139]
	v_pk_fma_f32 v[244:245], v[248:249], v[244:245], v[136:137]
	s_nop 0
	v_cvt_pk_bf16_f32 v244, v244, v245
	v_cvt_pk_bf16_f32 v245, v242, v243
	global_store_dwordx2 v[240:241], v[244:245], off offset:1536
	s_cbranch_execz .LBB0_765
